# v46 + in-proj writes its four m-groups in reverse order so post_z (ascending tokens) starts on the most recently written part of z
# baseline (speedup 1.0000x reference)
; DI int TID8() { int t = threadIdx.x; asm volatile("" : "+v"(t)); return t; }
; DI void gemm8_accum(f32x4 (&acc)[8][4], const bf16_t* a, size_t lda, const bf16_t* b, size_t ldb, int nkb, bf16_t* L,
;                     const bool pre, const bf16_t* an, size_t ldan, const bf16_t* bn, size_t ldbn) {
;   const int tid = TID8(), lane = tid & 63, w = tid >> 6;
;   const int wm = w >> 2, wn = w & 3;
;   const int lrow = tid >> 3, lch = tid & 7;
;   u32x4 ra[4], rb[4];
;   unsigned offa[4], offb[4];
; #pragma unroll
;   for (int i = 0; i < 4; ++i) {
;     offa[i] = (unsigned)(lrow + 64 * i) * (unsigned)lda + (unsigned)(lch * 8);
;     offb[i] = (unsigned)(lrow + 64 * i) * (unsigned)ldb + (unsigned)(lch * 8);
;   }
;   if (!pre) {
;     g8_load1o(ra, a, offa);
;     g8_load1o(rb, b, offb);
;     __syncthreads();
;     g8_store(L, ra, rb, lrow, lch);
;   }
.LBB0_129:
	s_mul_hi_u32 s0, s10, 0xba2e8ba3
	s_lshr_b32 s0, s0, 6
	s_lshl_b32 s11, s0, 5
	s_xor_b32 s11, s11, 0x60
	s_mulk_i32 s0, 0x58
	s_sub_i32 s0, s10, s0
	s_and_b32 s12, s0, 3
	s_or_b32 s1, s11, s12
	s_or_b32 s5, s1, s38
	s_lshl_b32 s0, s0, 6
	s_and_b32 s9, s0, 0x1f00
	s_lshl_b32 s0, s5, 19
	v_mov_b32_e32 v36, v196
	s_add_u32 s2, s18, s0
	s_addc_u32 s3, s19, 0
	v_ashrrev_i32_e32 v8, 3, v36
	v_lshlrev_b32_e32 v0, 3, v36
	s_lshl_b32 s13, s9, 11
	v_and_b32_e32 v34, 56, v0
	v_lshlrev_b32_e32 v35, 10, v8
	s_add_u32 s0, s94, s13
	v_or_b32_e32 v2, v35, v34
	v_mov_b32_e32 v3, v1
	s_addc_u32 s1, s95, 0
	v_lshlrev_b64 v[164:165], 1, v[2:3]
	v_lshrrev_b32_e32 v7, 1, v8
	v_add_u32_e32 v168, 0x10000, v2
	v_add_u32_e32 v166, 0x20000, v2
	v_add_u32_e32 v0, 0x30000, v2
	v_mov_b32_e32 v167, v1
	v_mov_b32_e32 v169, v1
	s_andn2_b64 vcc, exec, s[6:7]
	v_lshl_add_u64 v[4:5], s[2:3], 0, v[164:165]
	v_lshl_add_u64 v[2:3], s[0:1], 0, v[164:165]
	v_lshlrev_b32_e32 v6, 6, v8
	v_xor_b32_e32 v7, v7, v36
	s_cbranch_vccz .LBB0_131
	v_lshlrev_b64 v[26:27], 1, v[168:169]
	v_lshlrev_b64 v[38:39], 1, v[166:167]
	v_lshlrev_b64 v[44:45], 1, v[0:1]
	v_lshl_add_u64 v[10:11], s[2:3], 0, v[26:27]
	v_lshl_add_u64 v[14:15], s[2:3], 0, v[38:39]
	v_lshl_add_u64 v[28:29], s[2:3], 0, v[44:45]
	v_lshl_add_u64 v[30:31], s[0:1], 0, v[26:27]
	global_load_dwordx4 v[10:13], v[10:11], off
	s_nop 0
	global_load_dwordx4 v[14:17], v[14:15], off
	s_nop 0
	global_load_dwordx4 v[18:21], v[4:5], off
	global_load_dwordx4 v[22:25], v[2:3], off
	s_nop 0
	global_load_dwordx4 v[26:29], v[28:29], off
	s_nop 0
	global_load_dwordx4 v[30:33], v[30:31], off
	v_lshl_add_u64 v[38:39], s[0:1], 0, v[38:39]
	global_load_dwordx4 v[40:43], v[38:39], off
	v_lshl_add_u64 v[38:39], s[0:1], 0, v[44:45]
	global_load_dwordx4 v[44:47], v[38:39], off
	v_lshlrev_b32_e32 v37, 6, v8
	v_lshlrev_b32_e32 v8, 3, v7
	v_and_b32_e32 v38, 56, v8
	v_or_b32_e32 v8, v38, v37
	v_lshl_add_u32 v8, v8, 1, 0
	s_barrier
	s_waitcnt vmcnt(5)
	ds_write_b128 v8, v[18:21]
	s_waitcnt vmcnt(4)
	ds_write_b128 v8, v[22:25] offset:32768
	ds_write_b128 v8, v[10:13] offset:8192
	s_waitcnt vmcnt(2)
	ds_write_b128 v8, v[30:33] offset:40960
	ds_write_b128 v8, v[14:17] offset:16384
	s_waitcnt vmcnt(1)
	ds_write_b128 v8, v[40:43] offset:49152
	ds_write_b128 v8, v[26:29] offset:24576
	s_waitcnt vmcnt(0)
	ds_write_b128 v8, v[44:47] offset:57344
	s_cbranch_execz .LBB0_132
	s_branch .LBB0_133

; DI void gemm8_accum(f32x4 (&acc)[8][4], const bf16_t* a, size_t lda, const bf16_t* b, size_t ldb, int nkb, bf16_t* L,
;                     const bool pre, const bf16_t* an, size_t ldan, const bf16_t* bn, size_t ldbn) {
;     ...
;   __syncthreads();
;   g8_store1(L + 32768, ra, lrow, lch);
;   g8_load1(ra, an, ldan, 0, lrow, lch);
;   __builtin_amdgcn_sched_barrier(0);
;   g8_compute<0, 1>(acc, L, wm, wn, lane);
;   __builtin_amdgcn_sched_barrier(0);
;   g8_store1(L + 32768 + 16384, rb, lrow, lch);
;   g8_load1(rb, bn, ldbn, 0, lrow, lch);
;   __builtin_amdgcn_sched_barrier(0);
;   g8_compute<1, 2>(acc, L, wm, wn, lane);
.Lstg_134_c:
	v_readlane_b32 s0, v254, 18
	s_add_i32 s11, s10, s0
	s_cmpk_gt_u32 s11, 0x15f
	s_cselect_b64 s[0:1], -1, 0
	s_cmpk_lt_u32 s11, 0x160
	s_cselect_b32 s2, s11, s10
	s_mul_hi_u32 s3, s2, 0xba2e8ba3
	s_lshr_b32 s3, s3, 6
	s_lshl_b32 s6, s3, 5
	s_xor_b32 s6, s6, 0x60
	s_mulk_i32 s3, 0x58
	s_sub_i32 s7, s2, s3
	s_and_b32 s2, s7, 3
	s_or_b32 s2, s6, s2
	s_or_b32 s28, s2, s38
	s_lshl_b64 s[2:3], s[28:29], 19
	s_add_u32 s2, s18, s2
	v_mov_b32_e32 v169, v1
	v_mov_b32_e32 v167, v1
	s_addc_u32 s3, s19, s3
	v_lshlrev_b64 v[184:185], 1, v[168:169]
	v_lshlrev_b64 v[166:167], 1, v[166:167]
	v_lshlrev_b64 v[198:199], 1, v[0:1]
	v_lshl_add_u64 v[170:171], s[2:3], 0, v[164:165]
	v_lshl_add_u64 v[172:173], s[2:3], 0, v[184:185]
	v_lshl_add_u64 v[176:177], s[2:3], 0, v[166:167]
	v_lshl_add_u64 v[180:181], s[2:3], 0, v[198:199]
	s_barrier
	global_load_dwordx4 v[168:171], v[170:171], off
	s_nop 0
	global_load_dwordx4 v[172:175], v[172:173], off
	s_nop 0
	global_load_dwordx4 v[176:179], v[176:177], off
	s_nop 0
	global_load_dwordx4 v[180:183], v[180:181], off
	s_lshl_b32 s2, s7, 17
	s_and_b32 s2, s2, 0xf80000
	s_add_u32 s2, s94, s2
	s_addc_u32 s3, s95, 0
	s_add_i32 s6, 0, 0x10000
	v_add3_u32 v0, s6, v189, v190
	s_waitcnt vmcnt(11)
	ds_write_b128 v0, v[22:25]
	s_waitcnt vmcnt(9)
	ds_write_b128 v0, v[18:21] offset:8192
	ds_write_b128 v0, v[26:29] offset:16384
	s_waitcnt vmcnt(8)
	ds_write_b128 v0, v[30:33] offset:24576
	v_lshlrev_b32_e32 v0, 1, v191
	v_add_u32_e32 v191, 0, v0
	v_add_u32_e32 v200, v191, v187
	ds_read_b128 v[18:21], v200
	ds_read_b128 v[22:25], v200 offset:2048
	ds_read_b128 v[26:29], v200 offset:4096
	ds_read_b128 v[30:33], v200 offset:6144
	ds_read_b128 v[192:195], v200 offset:8192
	ds_read_b128 v[206:209], v200 offset:10240
	ds_read_b128 v[210:213], v200 offset:12288
	ds_read_b128 v[214:217], v200 offset:14336
	v_add_u32_e32 v191, v191, v186
	ds_read_b128 v[218:221], v191 offset:32768
	ds_read_b128 v[222:225], v191 offset:34816
	ds_read_b128 v[226:229], v191 offset:36864
	ds_read_b128 v[230:233], v191 offset:38912
	s_waitcnt lgkmcnt(3)
	v_mfma_f32_16x16x32_bf16 v[34:37], v[218:221], v[18:21], v[34:37]
	s_waitcnt lgkmcnt(2)
	v_mfma_f32_16x16x32_bf16 v[38:41], v[222:225], v[18:21], v[38:41]
	s_waitcnt lgkmcnt(1)
	v_mfma_f32_16x16x32_bf16 v[42:45], v[226:229], v[18:21], v[42:45]
	s_waitcnt lgkmcnt(0)
	v_mfma_f32_16x16x32_bf16 v[18:21], v[230:233], v[18:21], v[46:49]
	v_mfma_f32_16x16x32_bf16 v[46:49], v[218:221], v[22:25], v[50:53]
	v_mfma_f32_16x16x32_bf16 v[50:53], v[222:225], v[22:25], v[54:57]
	v_mfma_f32_16x16x32_bf16 v[54:57], v[226:229], v[22:25], v[58:61]
	v_mfma_f32_16x16x32_bf16 v[22:25], v[230:233], v[22:25], v[62:65]
	v_mfma_f32_16x16x32_bf16 v[58:61], v[218:221], v[26:29], v[66:69]
	v_mfma_f32_16x16x32_bf16 v[62:65], v[222:225], v[26:29], v[70:73]
	v_mfma_f32_16x16x32_bf16 v[66:69], v[226:229], v[26:29], v[74:77]
	v_mfma_f32_16x16x32_bf16 v[26:29], v[230:233], v[26:29], v[78:81]
	v_mfma_f32_16x16x32_bf16 v[70:73], v[218:221], v[30:33], v[82:85]
	v_mfma_f32_16x16x32_bf16 v[74:77], v[222:225], v[30:33], v[86:89]
	v_mfma_f32_16x16x32_bf16 v[78:81], v[226:229], v[30:33], v[90:93]
	v_mfma_f32_16x16x32_bf16 v[30:33], v[230:233], v[30:33], v[94:97]
	v_mfma_f32_16x16x32_bf16 v[82:85], v[218:221], v[192:195], v[98:101]
	v_mfma_f32_16x16x32_bf16 v[86:89], v[222:225], v[192:195], v[102:105]
	v_mfma_f32_16x16x32_bf16 v[90:93], v[226:229], v[192:195], v[106:109]
	v_mfma_f32_16x16x32_bf16 v[94:97], v[230:233], v[192:195], v[110:113]
	v_mfma_f32_16x16x32_bf16 v[98:101], v[218:221], v[206:209], v[114:117]
	v_mfma_f32_16x16x32_bf16 v[102:105], v[222:225], v[206:209], v[118:121]
	v_mfma_f32_16x16x32_bf16 v[106:109], v[226:229], v[206:209], v[122:125]
	v_mfma_f32_16x16x32_bf16 v[110:113], v[230:233], v[206:209], v[126:129]
	v_mfma_f32_16x16x32_bf16 v[114:117], v[218:221], v[210:213], v[130:133]
	v_mfma_f32_16x16x32_bf16 v[118:121], v[222:225], v[210:213], v[134:137]
	v_mfma_f32_16x16x32_bf16 v[122:125], v[226:229], v[210:213], v[138:141]
	v_mfma_f32_16x16x32_bf16 v[126:129], v[230:233], v[210:213], v[142:145]
	v_mfma_f32_16x16x32_bf16 v[130:133], v[218:221], v[214:217], v[146:149]
	v_mfma_f32_16x16x32_bf16 v[134:137], v[222:225], v[214:217], v[150:153]
	v_mfma_f32_16x16x32_bf16 v[138:141], v[226:229], v[214:217], v[154:157]
	v_mfma_f32_16x16x32_bf16 v[142:145], v[230:233], v[214:217], v[158:161]
	v_readlane_b32 s7, v254, 36
	s_nop 1
	v_add3_u32 v146, s7, v189, v190
	s_waitcnt vmcnt(7)
	ds_write_b128 v146, v[6:9]
	s_waitcnt vmcnt(6)
	ds_write_b128 v146, v[2:5] offset:8192
	s_waitcnt vmcnt(5)
	ds_write_b128 v146, v[10:13] offset:16384
	s_waitcnt vmcnt(4)
	ds_write_b128 v146, v[14:17] offset:24576
	v_lshl_add_u64 v[2:3], s[2:3], 0, v[164:165]
	v_lshl_add_u64 v[6:7], s[2:3], 0, v[184:185]
	v_lshl_add_u64 v[10:11], s[2:3], 0, v[166:167]
	v_lshl_add_u64 v[14:15], s[2:3], 0, v[198:199]
	global_load_dwordx4 v[2:5], v[2:3], off
	s_nop 0
	global_load_dwordx4 v[6:9], v[6:7], off
	s_nop 0
	global_load_dwordx4 v[10:13], v[10:11], off
	s_nop 0
	global_load_dwordx4 v[14:17], v[14:15], off
	v_lshlrev_b32_e32 v184, 1, v188
	v_add_u32_e32 v185, 0, v184
	v_add_u32_e32 v198, v185, v187
	ds_read_b128 v[146:149], v198
	ds_read_b128 v[150:153], v198 offset:2048
	ds_read_b128 v[154:157], v198 offset:4096
	ds_read_b128 v[158:161], v198 offset:6144
	ds_read_b128 v[164:167], v198 offset:8192
	ds_read_b128 v[188:191], v198 offset:10240
	ds_read_b128 v[192:195], v198 offset:12288
	ds_read_b128 v[206:209], v198 offset:14336
	v_add_u32_e32 v185, v185, v186
	ds_read_b128 v[210:213], v185 offset:32768
	ds_read_b128 v[214:217], v185 offset:34816
	ds_read_b128 v[218:221], v185 offset:36864
	ds_read_b128 v[222:225], v185 offset:38912
	s_waitcnt lgkmcnt(3)
; DI void gemm8_accum(f32x4 (&acc)[8][4], const bf16_t* a, size_t lda, const bf16_t* b, size_t ldb, int nkb, bf16_t* L,
;                     const bool pre, const bf16_t* an, size_t ldan, const bf16_t* bn, size_t ldbn) {
;     ...
;   g8_compute<1, 2>(acc, L, wm, wn, lane);
;   __syncthreads();
;   g8_store1(L, ra, lrow, lch);
;   __builtin_amdgcn_sched_barrier(0);
;   g8_compute<0, 1>(acc, L + 32768, wm, wn, lane);
;   __builtin_amdgcn_sched_barrier(0);
;   g8_store1(L + 16384, rb, lrow, lch);
	v_mfma_f32_16x16x32_bf16 v[34:37], v[210:213], v[146:149], v[34:37]
	s_waitcnt lgkmcnt(2)
	v_mfma_f32_16x16x32_bf16 v[38:41], v[214:217], v[146:149], v[38:41]
	s_waitcnt lgkmcnt(1)
	v_mfma_f32_16x16x32_bf16 v[42:45], v[218:221], v[146:149], v[42:45]
	s_waitcnt lgkmcnt(0)
	v_mfma_f32_16x16x32_bf16 v[18:21], v[222:225], v[146:149], v[18:21]
	v_mfma_f32_16x16x32_bf16 v[46:49], v[210:213], v[150:153], v[46:49]
	v_mfma_f32_16x16x32_bf16 v[50:53], v[214:217], v[150:153], v[50:53]
	v_mfma_f32_16x16x32_bf16 v[54:57], v[218:221], v[150:153], v[54:57]
	v_mfma_f32_16x16x32_bf16 v[22:25], v[222:225], v[150:153], v[22:25]
	v_mfma_f32_16x16x32_bf16 v[58:61], v[210:213], v[154:157], v[58:61]
	v_mfma_f32_16x16x32_bf16 v[62:65], v[214:217], v[154:157], v[62:65]
	v_mfma_f32_16x16x32_bf16 v[66:69], v[218:221], v[154:157], v[66:69]
	v_mfma_f32_16x16x32_bf16 v[26:29], v[222:225], v[154:157], v[26:29]
	v_mfma_f32_16x16x32_bf16 v[70:73], v[210:213], v[158:161], v[70:73]
	v_mfma_f32_16x16x32_bf16 v[74:77], v[214:217], v[158:161], v[74:77]
	v_mfma_f32_16x16x32_bf16 v[30:33], v[222:225], v[158:161], v[30:33]
	v_mfma_f32_16x16x32_bf16 v[78:81], v[218:221], v[158:161], v[78:81]
	v_mfma_f32_16x16x32_bf16 v[82:85], v[210:213], v[164:167], v[82:85]
	v_mfma_f32_16x16x32_bf16 v[86:89], v[214:217], v[164:167], v[86:89]
	v_mfma_f32_16x16x32_bf16 v[90:93], v[218:221], v[164:167], v[90:93]
	v_mfma_f32_16x16x32_bf16 v[94:97], v[222:225], v[164:167], v[94:97]
	v_mfma_f32_16x16x32_bf16 v[98:101], v[210:213], v[188:191], v[98:101]
	v_mfma_f32_16x16x32_bf16 v[102:105], v[214:217], v[188:191], v[102:105]
	v_mfma_f32_16x16x32_bf16 v[106:109], v[218:221], v[188:191], v[106:109]
	v_mfma_f32_16x16x32_bf16 v[110:113], v[222:225], v[188:191], v[110:113]
	v_mfma_f32_16x16x32_bf16 v[114:117], v[210:213], v[192:195], v[114:117]
	v_mfma_f32_16x16x32_bf16 v[118:121], v[214:217], v[192:195], v[118:121]
	v_mfma_f32_16x16x32_bf16 v[122:125], v[218:221], v[192:195], v[122:125]
	v_mfma_f32_16x16x32_bf16 v[126:129], v[222:225], v[192:195], v[126:129]
	v_mfma_f32_16x16x32_bf16 v[130:133], v[210:213], v[206:209], v[130:133]
	v_mfma_f32_16x16x32_bf16 v[134:137], v[214:217], v[206:209], v[134:137]
	v_mfma_f32_16x16x32_bf16 v[138:141], v[218:221], v[206:209], v[138:141]
	v_mfma_f32_16x16x32_bf16 v[142:145], v[222:225], v[206:209], v[142:145]
	s_barrier
	s_waitcnt vmcnt(7)
	ds_write_b128 v163, v[168:171]
	s_waitcnt vmcnt(6)
	ds_write_b128 v163, v[172:175] offset:8192
	s_waitcnt vmcnt(5)
	ds_write_b128 v163, v[176:179] offset:16384
	s_waitcnt vmcnt(4)
	ds_write_b128 v163, v[180:183] offset:24576
	v_add3_u32 v176, s6, v0, v187
	ds_read_b128 v[146:149], v176
	ds_read_b128 v[150:153], v176 offset:2048
	ds_read_b128 v[154:157], v176 offset:4096
	ds_read_b128 v[158:161], v176 offset:6144
	ds_read_b128 v[164:167], v176 offset:8192
	ds_read_b128 v[168:171], v176 offset:10240
	ds_read_b128 v[172:175], v176 offset:12288
	ds_read_b128 v[176:179], v176 offset:14336
	v_add3_u32 v0, s7, v0, v186
	ds_read_b128 v[180:183], v0
	ds_read_b128 v[188:191], v0 offset:2048
	ds_read_b128 v[192:195], v0 offset:4096
	ds_read_b128 v[206:209], v0 offset:6144
	s_waitcnt lgkmcnt(3)
	v_mfma_f32_16x16x32_bf16 v[34:37], v[180:183], v[146:149], v[34:37]
	s_waitcnt lgkmcnt(2)
	v_mfma_f32_16x16x32_bf16 v[38:41], v[188:191], v[146:149], v[38:41]
	s_waitcnt lgkmcnt(1)
	v_mfma_f32_16x16x32_bf16 v[42:45], v[192:195], v[146:149], v[42:45]
	s_waitcnt lgkmcnt(0)
	v_mfma_f32_16x16x32_bf16 v[18:21], v[206:209], v[146:149], v[18:21]
	v_mfma_f32_16x16x32_bf16 v[46:49], v[180:183], v[150:153], v[46:49]
	v_mfma_f32_16x16x32_bf16 v[50:53], v[188:191], v[150:153], v[50:53]
	v_mfma_f32_16x16x32_bf16 v[54:57], v[192:195], v[150:153], v[54:57]
	v_mfma_f32_16x16x32_bf16 v[22:25], v[206:209], v[150:153], v[22:25]
	v_mfma_f32_16x16x32_bf16 v[58:61], v[180:183], v[154:157], v[58:61]
	v_mfma_f32_16x16x32_bf16 v[62:65], v[188:191], v[154:157], v[62:65]
	v_mfma_f32_16x16x32_bf16 v[66:69], v[192:195], v[154:157], v[66:69]
	v_mfma_f32_16x16x32_bf16 v[26:29], v[206:209], v[154:157], v[26:29]
	v_mfma_f32_16x16x32_bf16 v[70:73], v[180:183], v[158:161], v[70:73]
	v_mfma_f32_16x16x32_bf16 v[74:77], v[188:191], v[158:161], v[74:77]
	v_mfma_f32_16x16x32_bf16 v[30:33], v[206:209], v[158:161], v[30:33]
	v_mfma_f32_16x16x32_bf16 v[78:81], v[192:195], v[158:161], v[78:81]
	v_mfma_f32_16x16x32_bf16 v[82:85], v[180:183], v[164:167], v[82:85]
	v_mfma_f32_16x16x32_bf16 v[86:89], v[188:191], v[164:167], v[86:89]
	v_mfma_f32_16x16x32_bf16 v[90:93], v[192:195], v[164:167], v[90:93]
	v_mfma_f32_16x16x32_bf16 v[94:97], v[206:209], v[164:167], v[94:97]
	v_mfma_f32_16x16x32_bf16 v[98:101], v[180:183], v[168:171], v[98:101]
	v_mfma_f32_16x16x32_bf16 v[102:105], v[188:191], v[168:171], v[102:105]
	v_mfma_f32_16x16x32_bf16 v[106:109], v[192:195], v[168:171], v[106:109]
	v_mfma_f32_16x16x32_bf16 v[110:113], v[206:209], v[168:171], v[110:113]
	v_mfma_f32_16x16x32_bf16 v[114:117], v[180:183], v[172:175], v[114:117]
	v_mfma_f32_16x16x32_bf16 v[118:121], v[188:191], v[172:175], v[118:121]
	v_mfma_f32_16x16x32_bf16 v[122:125], v[192:195], v[172:175], v[122:125]
	v_mfma_f32_16x16x32_bf16 v[126:129], v[206:209], v[172:175], v[126:129]
	v_mfma_f32_16x16x32_bf16 v[130:133], v[180:183], v[176:179], v[130:133]
	v_mfma_f32_16x16x32_bf16 v[134:137], v[188:191], v[176:179], v[134:137]
	v_mfma_f32_16x16x32_bf16 v[138:141], v[192:195], v[176:179], v[138:141]
	v_mfma_f32_16x16x32_bf16 v[142:145], v[206:209], v[176:179], v[142:145]
	s_waitcnt vmcnt(3)
	ds_write_b128 v163, v[2:5] offset:32768
	s_waitcnt vmcnt(2)
	ds_write_b128 v163, v[6:9] offset:40960
	s_waitcnt vmcnt(1)
	ds_write_b128 v163, v[10:13] offset:49152
	s_waitcnt vmcnt(0)
; DI int TID8() { int t = threadIdx.x; asm volatile("" : "+v"(t)); return t; }
; DI void gemm8_accum(f32x4 (&acc)[8][4], const bf16_t* a, size_t lda, const bf16_t* b, size_t ldb, int nkb, bf16_t* L,
;                     const bool pre, const bf16_t* an, size_t ldan, const bf16_t* bn, size_t ldbn) {
;     ...
;   g8_store1(L + 16384, rb, lrow, lch);
;   __builtin_amdgcn_sched_barrier(0);
;   g8_compute<1, 2>(acc, L + 32768, wm, wn, lane);
;   __syncthreads();
; template <class F>
; DI void gemm8_epi_staged(f32x4 (&acc)[8][4], int m0, int n0, bf16_t* L0, F f, bf16_t* dst, size_t ld, int nmax) {
;   bf16_t* L = L0 + 32768;
;   const int tid = TID8(), lane = tid & 63, w = tid >> 6;
;   const int wm = w >> 2, wn = w & 3;
; #pragma unroll
;   for (int half = 0; half < 2; ++half) {
;     if (wm == half) {
; #pragma unroll
;       for (int i = 0; i < 8; ++i)
; #pragma unroll
;         for (int j = 0; j < 4; ++j) {
;           const int ml = i * 16 + (lane & 15);
;           const int nl = wn * 64 + j * 16 + (lane >> 4) * 4;
;           f32x4 a = acc[i][j];
;           f(m0 + half * 128 + ml, n0 + nl, a);
;           uint2 u;
;           u.x = pack2(a[0], a[1]);
;           u.y = pack2(a[2], a[3]);
;           *(uint2*)(L + ml * 264 + nl) = u;
;         }
;     }
	ds_write_b128 v163, v[14:17] offset:57344
	v_add3_u32 v0, s6, v184, v187
	ds_read_b128 v[2:5], v0
	ds_read_b128 v[6:9], v0 offset:2048
	ds_read_b128 v[10:13], v0 offset:4096
	ds_read_b128 v[14:17], v0 offset:6144
	ds_read_b128 v[146:149], v0 offset:8192
	ds_read_b128 v[150:153], v0 offset:10240
	ds_read_b128 v[154:157], v0 offset:12288
	ds_read_b128 v[158:161], v0 offset:14336
	v_add3_u32 v0, s7, v184, v186
	ds_read_b128 v[164:167], v0
	ds_read_b128 v[168:171], v0 offset:2048
	ds_read_b128 v[172:175], v0 offset:4096
	ds_read_b128 v[176:179], v0 offset:6144
	s_waitcnt lgkmcnt(3)
	v_mfma_f32_16x16x32_bf16 v[34:37], v[164:167], v[2:5], v[34:37]
	s_waitcnt lgkmcnt(2)
	v_mfma_f32_16x16x32_bf16 v[38:41], v[168:171], v[2:5], v[38:41]
	s_waitcnt lgkmcnt(1)
	v_mfma_f32_16x16x32_bf16 v[42:45], v[172:175], v[2:5], v[42:45]
	s_waitcnt lgkmcnt(0)
	v_mfma_f32_16x16x32_bf16 v[2:5], v[176:179], v[2:5], v[18:21]
	v_mfma_f32_16x16x32_bf16 v[18:21], v[164:167], v[6:9], v[46:49]
	v_mfma_f32_16x16x32_bf16 v[50:53], v[168:171], v[6:9], v[50:53]
	v_mfma_f32_16x16x32_bf16 v[180:183], v[172:175], v[6:9], v[54:57]
	v_mfma_f32_16x16x32_bf16 v[6:9], v[176:179], v[6:9], v[22:25]
	v_mfma_f32_16x16x32_bf16 v[22:25], v[164:167], v[10:13], v[58:61]
	v_mfma_f32_16x16x32_bf16 v[184:187], v[168:171], v[10:13], v[62:65]
	v_mfma_f32_16x16x32_bf16 v[66:69], v[172:175], v[10:13], v[66:69]
	v_mfma_f32_16x16x32_bf16 v[10:13], v[176:179], v[10:13], v[26:29]
	v_mfma_f32_16x16x32_bf16 v[26:29], v[164:167], v[14:17], v[70:73]
	v_mfma_f32_16x16x32_bf16 v[188:191], v[168:171], v[14:17], v[74:77]
	v_mfma_f32_16x16x32_bf16 v[78:81], v[172:175], v[14:17], v[78:81]
	v_mfma_f32_16x16x32_bf16 v[14:17], v[176:179], v[14:17], v[30:33]
	v_mfma_f32_16x16x32_bf16 v[82:85], v[164:167], v[146:149], v[82:85]
	v_mfma_f32_16x16x32_bf16 v[86:89], v[168:171], v[146:149], v[86:89]
	v_mfma_f32_16x16x32_bf16 v[90:93], v[172:175], v[146:149], v[90:93]
	v_mfma_f32_16x16x32_bf16 v[94:97], v[176:179], v[146:149], v[94:97]
	v_mfma_f32_16x16x32_bf16 v[98:101], v[164:167], v[150:153], v[98:101]
	v_mfma_f32_16x16x32_bf16 v[102:105], v[168:171], v[150:153], v[102:105]
	v_mfma_f32_16x16x32_bf16 v[106:109], v[172:175], v[150:153], v[106:109]
	v_mfma_f32_16x16x32_bf16 v[110:113], v[176:179], v[150:153], v[110:113]
	v_mfma_f32_16x16x32_bf16 v[114:117], v[164:167], v[154:157], v[114:117]
	v_mfma_f32_16x16x32_bf16 v[118:121], v[168:171], v[154:157], v[118:121]
	v_mfma_f32_16x16x32_bf16 v[122:125], v[172:175], v[154:157], v[122:125]
	v_mfma_f32_16x16x32_bf16 v[126:129], v[176:179], v[154:157], v[126:129]
	v_mfma_f32_16x16x32_bf16 v[130:133], v[164:167], v[158:161], v[130:133]
	v_mfma_f32_16x16x32_bf16 v[134:137], v[168:171], v[158:161], v[134:137]
	v_mfma_f32_16x16x32_bf16 v[138:141], v[172:175], v[158:161], v[138:141]
	v_mfma_f32_16x16x32_bf16 v[142:145], v[176:179], v[158:161], v[142:145]
	v_mov_b32_e32 v77, v196
	s_barrier
	s_movk_i32 s2, 0x100
	v_and_b32_e32 v0, 0xc0, v77
	v_lshrrev_b32_e32 v31, 1, v77
	v_lshlrev_b32_e32 v0, 1, v0
	v_and_b32_e32 v31, 24, v31
	v_and_b32_e32 v30, 15, v77
	v_add3_u32 v0, s6, v0, v31
	v_cmp_gt_u32_e32 vcc, s2, v77
	s_movk_i32 s2, 0x210
	v_mad_u32_u24 v72, v30, s2, v0
	v_cvt_pk_bf16_f32 v60, v34, v35
	v_cvt_pk_bf16_f32 v61, v36, v37
	v_cvt_pk_bf16_f32 v64, v38, v39
	v_cvt_pk_bf16_f32 v65, v40, v41
	v_cvt_pk_bf16_f32 v54, v42, v43
	v_cvt_pk_bf16_f32 v55, v44, v45
	v_cvt_pk_bf16_f32 v62, v2, v3
	v_cvt_pk_bf16_f32 v63, v4, v5
	v_cvt_pk_bf16_f32 v48, v18, v19
	v_cvt_pk_bf16_f32 v49, v20, v21
	v_cvt_pk_bf16_f32 v58, v50, v51
	v_cvt_pk_bf16_f32 v59, v52, v53
	v_add_u32_e32 v76, 0x2000, v72
	v_cvt_pk_bf16_f32 v46, v180, v181
	v_cvt_pk_bf16_f32 v47, v182, v183
	v_cvt_pk_bf16_f32 v56, v6, v7
	v_cvt_pk_bf16_f32 v57, v8, v9
	v_cvt_pk_bf16_f32 v40, v22, v23
	v_cvt_pk_bf16_f32 v41, v24, v25
	v_cvt_pk_bf16_f32 v52, v184, v185
	v_cvt_pk_bf16_f32 v53, v186, v187
	v_add_u32_e32 v75, 0x4000, v72
	v_cvt_pk_bf16_f32 v38, v66, v67
	v_cvt_pk_bf16_f32 v39, v68, v69
	v_cvt_pk_bf16_f32 v50, v10, v11
	v_cvt_pk_bf16_f32 v51, v12, v13
	v_cvt_pk_bf16_f32 v32, v26, v27
	v_cvt_pk_bf16_f32 v33, v28, v29
	v_cvt_pk_bf16_f32 v44, v188, v189
	v_cvt_pk_bf16_f32 v45, v190, v191
	v_add_u32_e32 v74, 0x6000, v72
	v_cvt_pk_bf16_f32 v30, v78, v79
	v_cvt_pk_bf16_f32 v31, v80, v81
	v_cvt_pk_bf16_f32 v42, v14, v15
	v_cvt_pk_bf16_f32 v43, v16, v17
	v_cvt_pk_bf16_f32 v24, v82, v83
	v_cvt_pk_bf16_f32 v25, v84, v85
	v_cvt_pk_bf16_f32 v36, v86, v87
	v_cvt_pk_bf16_f32 v37, v88, v89
	v_add_u32_e32 v73, 0x8000, v72
	v_cvt_pk_bf16_f32 v22, v90, v91
	v_cvt_pk_bf16_f32 v23, v92, v93
	v_cvt_pk_bf16_f32 v34, v94, v95
	v_cvt_pk_bf16_f32 v35, v96, v97
	v_cvt_pk_bf16_f32 v16, v98, v99
	v_cvt_pk_bf16_f32 v17, v100, v101
	v_cvt_pk_bf16_f32 v28, v102, v103
	v_cvt_pk_bf16_f32 v29, v104, v105
	v_add_u32_e32 v71, 0xa000, v72
	v_cvt_pk_bf16_f32 v14, v106, v107
	v_cvt_pk_bf16_f32 v15, v108, v109
	v_cvt_pk_bf16_f32 v26, v110, v111
	v_cvt_pk_bf16_f32 v27, v112, v113
	v_cvt_pk_bf16_f32 v8, v114, v115
	v_cvt_pk_bf16_f32 v9, v116, v117
	v_cvt_pk_bf16_f32 v20, v118, v119
	v_cvt_pk_bf16_f32 v21, v120, v121
	v_add_u32_e32 v70, 0xc000, v72
	v_cvt_pk_bf16_f32 v6, v122, v123
	v_cvt_pk_bf16_f32 v7, v124, v125
	v_cvt_pk_bf16_f32 v18, v126, v127
	v_cvt_pk_bf16_f32 v19, v128, v129
	v_cvt_pk_bf16_f32 v4, v130, v131
	v_cvt_pk_bf16_f32 v5, v132, v133
	v_cvt_pk_bf16_f32 v12, v134, v135
	v_cvt_pk_bf16_f32 v13, v136, v137
	v_add_u32_e32 v69, 0xe000, v72
	v_cvt_pk_bf16_f32 v2, v138, v139
	v_cvt_pk_bf16_f32 v3, v140, v141
	v_cvt_pk_bf16_f32 v10, v142, v143
	v_cvt_pk_bf16_f32 v11, v144, v145
	s_and_saveexec_b64 s[2:3], vcc
	s_cbranch_execz .LBB0_137
	ds_write2_b64 v72, v[60:61], v[64:65] offset1:4
	ds_write2_b64 v72, v[54:55], v[62:63] offset0:8 offset1:12
	ds_write2_b64 v76, v[48:49], v[58:59] offset0:32 offset1:36
	ds_write2_b64 v76, v[46:47], v[56:57] offset0:40 offset1:44
	ds_write2_b64 v75, v[40:41], v[52:53] offset0:64 offset1:68
	ds_write2_b64 v75, v[38:39], v[50:51] offset0:72 offset1:76
	ds_write2_b64 v74, v[32:33], v[44:45] offset0:96 offset1:100
	ds_write2_b64 v74, v[30:31], v[42:43] offset0:104 offset1:108
	ds_write2_b64 v73, v[24:25], v[36:37] offset0:128 offset1:132
	ds_write2_b64 v73, v[22:23], v[34:35] offset0:136 offset1:140
	ds_write2_b64 v71, v[16:17], v[28:29] offset0:160 offset1:164
	ds_write2_b64 v71, v[14:15], v[26:27] offset0:168 offset1:172
	ds_write2_b64 v70, v[8:9], v[20:21] offset0:192 offset1:196
	ds_write2_b64 v70, v[6:7], v[18:19] offset0:200 offset1:204
	ds_write2_b64 v69, v[4:5], v[12:13] offset0:224 offset1:228
	ds_write2_b64 v69, v[2:3], v[10:11] offset0:232 offset1:236
